# RWKV prompt loop: barrier between the chunk's output stage and the next chunk's staging removed (gate tile double-buffered in LDS, v kept in registers); code placement shifted by 56 bytes
# speedup vs baseline: 1.0120x; 1.0120x over previous
.LBB0_1228:
	s_or_b64 exec, exec, s[14:15]
	v_and_b32_e32 v59, 63, v56
	v_lshrrev_b32_e32 v60, 3, v59
	v_ashrrev_i32_e32 v59, 5, v56
	v_and_b32_e32 v93, 7, v56
	v_lshl_add_u32 v56, v63, 2, 0
	v_lshlrev_b32_e32 v63, 1, v63
	v_lshl_add_u32 v61, v67, 2, v56
	v_sub_u32_e32 v56, v56, v63
	v_lshlrev_b32_e32 v63, 1, v67
	v_lshlrev_b32_e32 v71, 8, v62
	v_lshlrev_b32_e32 v62, 7, v62
	v_lshlrev_b32_e32 v67, 2, v66
	v_add3_u32 v109, v56, v63, v62
	s_movk_i32 s24, 0x710
	v_lshl_or_b32 v63, v59, 6, v66
	v_add_u32_e32 v68, 0, v67
	v_mul_lo_u32 v56, v59, s24
	v_lshlrev_b32_e32 v66, 2, v63
	v_lshl_or_b32 v108, v57, 3, v60
	v_mov_b32_e32 v77, 0
	v_lshlrev_b32_e32 v69, 2, v65
	v_add_u32_e32 v62, 0, v56
	v_add_u32_e32 v92, 0, v66
	v_add_u32_e32 v111, v68, v56
	v_and_b32_e32 v56, 32, v174
	s_add_i32 s16, 0, 0x16200
	s_movk_i32 s17, 0xf8f4
	v_lshl_add_u64 v[90:91], s[12:13], 0, v[76:77]
	v_sub_u32_e32 v69, v68, v69
	v_cmp_eq_u32_e64 s[12:13], 0, v56
	v_add_u32_e32 v112, s16, v66
	v_mul_lo_u32 v56, v59, s17
	v_lshl_add_u32 v115, v108, 2, s16
	v_mad_u64_u32 v[94:95], s[16:17], v63, 28, v[92:93]
	v_lshl_add_u32 v113, v59, 7, v69
	v_cmp_gt_i32_e64 s[16:17], 16, v59
	v_add_u32_e32 v95, s3, v59
	v_mul_lo_u32 v59, v89, s24
	v_add_u32_e32 v66, 0, v59
	v_mov_b32_e32 v59, 0x1540
	v_mov_b32_e32 v68, s29
	v_cmp_gt_u32_e32 vcc, 24, v58
	v_add_u32_e32 v110, v62, v67
	v_lshlrev_b32_e32 v67, 5, v58
	v_cndmask_b32_e32 v59, v59, v68, vcc
	v_mov_b32_e32 v68, s28
	v_cmp_gt_u32_e32 vcc, 16, v58
	v_lshlrev_b32_e32 v70, 2, v93
	s_movk_i32 s25, 0xffe4
	v_cndmask_b32_e32 v59, v59, v68, vcc
	v_mov_b32_e32 v68, s5
	v_cmp_gt_i32_e32 vcc, 8, v58
	v_cmp_eq_u32_e64 s[14:15], 0, v65
	v_mul_u32_u24_e32 v65, 12, v93
	v_cndmask_b32_e32 v59, v59, v68, vcc
	v_lshl_add_u32 v58, v58, 3, v59
	v_ashrrev_i32_e32 v59, 31, v58
	v_lshl_add_u64 v[96:97], v[58:59], 1, s[22:23]
	v_mov_b32_e32 v58, 0x140
	v_cndmask_b32_e64 v76, v58, 64, s[18:19]
	v_mov_b32_e32 v58, 0x180
	v_mov_b32_e32 v59, 0x80
	v_cndmask_b32_e64 v98, v58, v59, s[18:19]
	v_mov_b32_e32 v58, 0x1c0
	v_mov_b32_e32 v59, 0xc0
	v_cndmask_b32_e64 v100, v58, v59, s[18:19]
	v_mov_b32_e32 v58, 0x100
	v_cndmask_b32_e64 v102, v58, 0, s[18:19]
	v_lshlrev_b32_e32 v58, 1, v64
	v_mov_b32_e32 v59, v77
	v_lshl_add_u64 v[106:107], s[20:21], 0, v[58:59]
	v_lshlrev_b32_e32 v58, 8, v57
	v_lshlrev_b32_e32 v59, 5, v60
	v_or3_b32 v58, v58, v59, v70
	v_mul_lo_u32 v63, v63, s25
	v_add_u32_e32 v116, 0xe200, v58
	s_movk_i32 s5, 0x7180
	v_lshlrev_b32_e32 v58, 2, v60
	s_mov_b32 s4, 0
	v_add3_u32 v114, 0, v70, v65
	v_mov_b32_e32 v99, v77
	v_mov_b32_e32 v101, v77
	v_mov_b32_e32 v103, v77
	s_waitcnt vmcnt(5)
	v_mov_b32_e32 v104, v85
	v_add3_u32 v117, v65, v70, s5
	v_lshl_or_b32 v118, v57, 5, v58
	v_add_u32_e32 v119, v66, v67
	s_movk_i32 s5, 0x800
	s_movk_i32 s28, 0x2e00
	s_mov_b32 s29, 0x800000
	v_mov_b32_e32 v120, 0x3a27c5ac
	v_add_u32_e32 v121, v94, v63
	v_add_u32_e32 v122, v61, v71
	v_add_u32_e32 v123, v62, v56
	v_mov_b32_e32 v127, v77
	v_mov_b32_e32 v126, v77
	v_mov_b32_e32 v125, v77
	v_mov_b32_e32 v124, v77
	s_nop 0
	s_nop 0
	s_nop 0
	s_nop 0
	s_nop 0
	s_nop 0
	s_nop 0
	s_nop 0
	s_nop 0
	s_nop 0
	s_nop 0
	s_nop 0
	s_nop 0
	s_nop 0
	s_nop 0
	s_mov_b32 s100, 0
	s_and_saveexec_b64 s[18:19], s[10:11]
	s_cbranch_execz .LBB0_1230

.LBB0_1236:
	s_nop 0
	ds_read2_b64 v[56:59], v110 offset0:32 offset1:64
	s_waitcnt lgkmcnt(0)
	v_mov_b32_e32 v162, v58
	v_mov_b32_e32 v163, v59
	v_pk_mul_f32 v[60:61], v[78:79], v[56:57]
	s_nop 0
	v_pk_mul_f32 v[62:63], v[60:61], v[60:61]
	v_cvt_pkrtz_f16_f32 v58, v58, v58
	v_add_f32_e32 v62, v62, v63
	v_cvt_pkrtz_f16_f32 v59, v59, v59
	ds_write_b64 v112, v[58:59]
	v_add_f32_dpp v62, v62, v62 quad_perm:[1,0,3,2] row_mask:0xf bank_mask:0xf bound_ctrl:1
	s_nop 1
	v_add_f32_dpp v62, v62, v62 quad_perm:[2,3,0,1] row_mask:0xf bank_mask:0xf bound_ctrl:1
	s_nop 1
	v_add_f32_dpp v62, v62, v62 row_half_mirror row_mask:0xf bank_mask:0xf bound_ctrl:1
	s_nop 1
	v_add_f32_dpp v62, v62, v62 row_mirror row_mask:0xf bank_mask:0xf bound_ctrl:1
	s_nop 0
	v_readlane_b32 s19, v62, 16
	v_readlane_b32 s23, v62, 48
	v_readlane_b32 s18, v62, 0
	v_readlane_b32 s22, v62, 32
	v_mov_b32_e32 v62, s19
	v_mov_b32_e32 v63, s23
	v_add_f32_e32 v62, s18, v62
	v_add_f32_e32 v63, s22, v63
	v_cndmask_b32_e64 v62, v63, v62, s[12:13]
	v_mul_f32_e32 v63, 0x4b800000, v62
	v_cmp_gt_f32_e32 vcc, s29, v62
	s_nop 1
	v_cndmask_b32_e32 v62, v62, v63, vcc
	v_rsq_f32_e32 v64, v62
	ds_read_b64 v[58:59], v111
	ds_read_b64 v[62:63], v92 offset:33024
	v_mul_f32_e32 v65, 0x45800000, v64
	v_cndmask_b32_e32 v64, v64, v65, vcc
	v_min_f32_e32 v64, 0x5368d4a5, v64
	v_pk_mul_f32 v[60:61], v[60:61], v[64:65] op_sel_hi:[1,0]
	s_nop 0
	v_cvt_pk_f16_f32 v64, v60, v61
	s_waitcnt lgkmcnt(0)
	v_pk_mul_f32 v[60:61], v[62:63], v[60:61]
	s_nop 0
	v_cvt_pk_f16_f32 v60, v60, v61
	ds_write2st64_b32 v113, v64, v60 offset0:161 offset1:177
	v_pk_add_f32 v[60:61], v[62:63], -1.0 op_sel_hi:[1,0]
	s_nop 0
	v_pk_fma_f32 v[60:61], v[80:81], v[60:61], 1.0 op_sel_hi:[1,1,0]
	s_nop 0
	v_pk_mul_f32 v[56:57], v[56:57], v[60:61]
	v_cvt_pk_f16_f32 v61, v58, v59
	v_cvt_pk_f16_f32 v60, v56, v57
	v_mul_f32_e32 v57, v59, v57
	v_mul_f32_e32 v56, v58, v56
	v_mul_f32_e32 v57, v83, v57
	v_fmac_f32_e32 v57, v82, v56
	ds_write2st64_b32 v113, v60, v61 offset0:193 offset1:209
	s_nop 0
	v_add_f32_dpp v56, v57, v57 quad_perm:[1,0,3,2] row_mask:0xf bank_mask:0xf bound_ctrl:1
	s_nop 1
	v_add_f32_dpp v56, v56, v56 quad_perm:[2,3,0,1] row_mask:0xf bank_mask:0xf bound_ctrl:1
	s_nop 1
	v_add_f32_dpp v56, v56, v56 row_half_mirror row_mask:0xf bank_mask:0xf bound_ctrl:1
	s_nop 1
	v_add_f32_dpp v56, v56, v56 row_mirror row_mask:0xf bank_mask:0xf bound_ctrl:1
	s_nop 0
	v_readlane_b32 s22, v56, 0
	v_readlane_b32 s24, v56, 16
	v_readlane_b32 s23, v56, 32
	v_readlane_b32 s25, v56, 48
	s_and_saveexec_b64 s[18:19], s[14:15]
	s_cbranch_execz .LBB0_1238
	v_mov_b32_e32 v56, s24
	v_mov_b32_e32 v57, s25
	v_add_f32_e32 v56, s22, v56
	v_add_f32_e32 v57, s23, v57
	v_cndmask_b32_e64 v56, v57, v56, s[12:13]
	ds_write_b32 v123, v56 offset:57600
.LBB0_1238:
	s_or_b64 exec, exec, s[18:19]
	s_waitcnt lgkmcnt(0)
	s_barrier
	ds_read_b128 v[72:75], v114 offset:41216
	ds_read_b128 v[68:71], v114 offset:45312
	ds_read_b128 v[64:67], v114 offset:49408
	ds_read_b128 v[56:59], v114 offset:53504
	ds_read_b128 v[60:63], v114 offset:28928
	ds_read_b32 v85, v115
	s_waitcnt lgkmcnt(0)
	v_dot2_f32_f16 v151, v127, v72, 0
	v_dot2_f32_f16 v151, v126, v73, v151
	v_dot2_f32_f16 v151, v125, v74, v151
	v_dot2_f32_f16 v151, v124, v75, v151
	ds_read_b128 v[134:137], v114 offset:41344
	ds_read_b128 v[138:141], v114 offset:45440
	ds_read_b128 v[142:145], v114 offset:49536
	v_add_f32_dpp v151, v151, v151 quad_perm:[1,0,3,2] row_mask:0xf bank_mask:0xf bound_ctrl:1
	ds_read_b128 v[130:133], v114 offset:29056
	ds_read_b128 v[146:149], v114 offset:53632
	v_add_f32_dpp v151, v151, v151 quad_perm:[2,3,0,1] row_mask:0xf bank_mask:0xf bound_ctrl:1
	ds_read_b32 v160, v115 offset:256
	s_nop 0
	v_add_f32_dpp v151, v151, v151 row_half_mirror row_mask:0xf bank_mask:0xf bound_ctrl:1
	v_cvt_pkrtz_f16_f32 v152, -v151, -v151
	v_pk_mul_f16 v153, v152, v68
	v_pk_mul_f16 v154, v152, v69
	v_pk_mul_f16 v155, v152, v70
	v_pk_mul_f16 v156, v152, v71
	v_pk_fma_f16 v153, v85, v64, v153
	v_pk_fma_f16 v154, v85, v65, v154
	v_pk_fma_f16 v155, v85, v66, v155
	v_pk_fma_f16 v156, v85, v67, v156
	v_pk_fma_f16 v127, v127, v60, v153
	v_pk_fma_f16 v126, v126, v61, v154
	v_pk_fma_f16 v125, v125, v62, v155
	v_pk_fma_f16 v124, v124, v63, v156
	v_dot2_f32_f16 v157, v127, v56, 0
	v_dot2_f32_f16 v157, v126, v57, v157
	v_dot2_f32_f16 v157, v125, v58, v157
	v_dot2_f32_f16 v157, v124, v59, v157
	s_waitcnt lgkmcnt(0)
	v_dot2_f32_f16 v151, v127, v134, 0
	v_dot2_f32_f16 v151, v126, v135, v151
	v_dot2_f32_f16 v151, v125, v136, v151
	v_dot2_f32_f16 v151, v124, v137, v151
	ds_read_b128 v[72:75], v114 offset:41472
	ds_read_b128 v[68:71], v114 offset:45568
	ds_read_b128 v[64:67], v114 offset:49664
	v_add_f32_dpp v151, v151, v151 quad_perm:[1,0,3,2] row_mask:0xf bank_mask:0xf bound_ctrl:1
	ds_read_b128 v[60:63], v114 offset:29184
	ds_read_b128 v[56:59], v114 offset:53760
	v_add_f32_dpp v151, v151, v151 quad_perm:[2,3,0,1] row_mask:0xf bank_mask:0xf bound_ctrl:1
	ds_read_b32 v85, v115 offset:512
	ds_write_b32 v116, v157 offset:0
	v_add_f32_dpp v151, v151, v151 row_half_mirror row_mask:0xf bank_mask:0xf bound_ctrl:1
	v_cvt_pkrtz_f16_f32 v152, -v151, -v151
	v_pk_mul_f16 v153, v152, v138
	v_pk_mul_f16 v154, v152, v139
	v_pk_mul_f16 v155, v152, v140
	v_pk_mul_f16 v156, v152, v141
	v_pk_fma_f16 v153, v160, v142, v153
	v_pk_fma_f16 v154, v160, v143, v154
	v_pk_fma_f16 v155, v160, v144, v155
	v_pk_fma_f16 v156, v160, v145, v156
	v_pk_fma_f16 v127, v127, v130, v153
	v_pk_fma_f16 v126, v126, v131, v154
	v_pk_fma_f16 v125, v125, v132, v155
	v_pk_fma_f16 v124, v124, v133, v156
	v_dot2_f32_f16 v158, v127, v146, 0
	v_dot2_f32_f16 v158, v126, v147, v158
	v_dot2_f32_f16 v158, v125, v148, v158
	v_dot2_f32_f16 v158, v124, v149, v158
	s_waitcnt lgkmcnt(0)
	v_dot2_f32_f16 v151, v127, v72, 0
	v_dot2_f32_f16 v151, v126, v73, v151
	v_dot2_f32_f16 v151, v125, v74, v151
	v_dot2_f32_f16 v151, v124, v75, v151
	ds_read_b128 v[134:137], v114 offset:41600
	ds_read_b128 v[138:141], v114 offset:45696
	ds_read_b128 v[142:145], v114 offset:49792
	v_add_f32_dpp v151, v151, v151 quad_perm:[1,0,3,2] row_mask:0xf bank_mask:0xf bound_ctrl:1
	ds_read_b128 v[130:133], v114 offset:29312
	ds_read_b128 v[146:149], v114 offset:53888
	v_add_f32_dpp v151, v151, v151 quad_perm:[2,3,0,1] row_mask:0xf bank_mask:0xf bound_ctrl:1
	ds_read_b32 v160, v115 offset:768
	ds_write_b32 v116, v158 offset:2048
	v_add_f32_dpp v151, v151, v151 row_half_mirror row_mask:0xf bank_mask:0xf bound_ctrl:1
	v_cvt_pkrtz_f16_f32 v152, -v151, -v151
	v_pk_mul_f16 v153, v152, v68
	v_pk_mul_f16 v154, v152, v69
	v_pk_mul_f16 v155, v152, v70
	v_pk_mul_f16 v156, v152, v71
	v_pk_fma_f16 v153, v85, v64, v153
	v_pk_fma_f16 v154, v85, v65, v154
	v_pk_fma_f16 v155, v85, v66, v155
	v_pk_fma_f16 v156, v85, v67, v156
	v_pk_fma_f16 v127, v127, v60, v153
	v_pk_fma_f16 v126, v126, v61, v154
	v_pk_fma_f16 v125, v125, v62, v155
	v_pk_fma_f16 v124, v124, v63, v156
	v_dot2_f32_f16 v157, v127, v56, 0
	v_dot2_f32_f16 v157, v126, v57, v157
	v_dot2_f32_f16 v157, v125, v58, v157
	v_dot2_f32_f16 v157, v124, v59, v157
	s_waitcnt lgkmcnt(0)
	v_dot2_f32_f16 v151, v127, v134, 0
	v_dot2_f32_f16 v151, v126, v135, v151
	v_dot2_f32_f16 v151, v125, v136, v151
	v_dot2_f32_f16 v151, v124, v137, v151
	ds_read_b128 v[72:75], v114 offset:41728
	ds_read_b128 v[68:71], v114 offset:45824
	ds_read_b128 v[64:67], v114 offset:49920
	v_add_f32_dpp v151, v151, v151 quad_perm:[1,0,3,2] row_mask:0xf bank_mask:0xf bound_ctrl:1
	ds_read_b128 v[60:63], v114 offset:29440
	ds_read_b128 v[56:59], v114 offset:54016
	v_add_f32_dpp v151, v151, v151 quad_perm:[2,3,0,1] row_mask:0xf bank_mask:0xf bound_ctrl:1
	ds_read_b32 v85, v115 offset:1024
	ds_write_b32 v116, v157 offset:4096
	v_add_f32_dpp v151, v151, v151 row_half_mirror row_mask:0xf bank_mask:0xf bound_ctrl:1
	v_cvt_pkrtz_f16_f32 v152, -v151, -v151
	v_pk_mul_f16 v153, v152, v138
	v_pk_mul_f16 v154, v152, v139
	v_pk_mul_f16 v155, v152, v140
	v_pk_mul_f16 v156, v152, v141
	v_pk_fma_f16 v153, v160, v142, v153
	v_pk_fma_f16 v154, v160, v143, v154
	v_pk_fma_f16 v155, v160, v144, v155
	v_pk_fma_f16 v156, v160, v145, v156
	v_pk_fma_f16 v127, v127, v130, v153
	v_pk_fma_f16 v126, v126, v131, v154
	v_pk_fma_f16 v125, v125, v132, v155
	v_pk_fma_f16 v124, v124, v133, v156
	v_dot2_f32_f16 v158, v127, v146, 0
	v_dot2_f32_f16 v158, v126, v147, v158
	v_dot2_f32_f16 v158, v125, v148, v158
	v_dot2_f32_f16 v158, v124, v149, v158
	s_waitcnt lgkmcnt(0)
	v_dot2_f32_f16 v151, v127, v72, 0
	v_dot2_f32_f16 v151, v126, v73, v151
	v_dot2_f32_f16 v151, v125, v74, v151
	v_dot2_f32_f16 v151, v124, v75, v151
	ds_read_b128 v[134:137], v114 offset:41856
	ds_read_b128 v[138:141], v114 offset:45952
	ds_read_b128 v[142:145], v114 offset:50048
	v_add_f32_dpp v151, v151, v151 quad_perm:[1,0,3,2] row_mask:0xf bank_mask:0xf bound_ctrl:1
	ds_read_b128 v[130:133], v114 offset:29568
	ds_read_b128 v[146:149], v114 offset:54144
	v_add_f32_dpp v151, v151, v151 quad_perm:[2,3,0,1] row_mask:0xf bank_mask:0xf bound_ctrl:1
	ds_read_b32 v160, v115 offset:1280
	ds_write_b32 v116, v158 offset:6144
	v_add_f32_dpp v151, v151, v151 row_half_mirror row_mask:0xf bank_mask:0xf bound_ctrl:1
	v_cvt_pkrtz_f16_f32 v152, -v151, -v151
	v_pk_mul_f16 v153, v152, v68
	v_pk_mul_f16 v154, v152, v69
	v_pk_mul_f16 v155, v152, v70
	v_pk_mul_f16 v156, v152, v71
	v_pk_fma_f16 v153, v85, v64, v153
	v_pk_fma_f16 v154, v85, v65, v154
	v_pk_fma_f16 v155, v85, v66, v155
	v_pk_fma_f16 v156, v85, v67, v156
	v_pk_fma_f16 v127, v127, v60, v153
	v_pk_fma_f16 v126, v126, v61, v154
	v_pk_fma_f16 v125, v125, v62, v155
	v_pk_fma_f16 v124, v124, v63, v156
	v_dot2_f32_f16 v157, v127, v56, 0
	v_dot2_f32_f16 v157, v126, v57, v157
	v_dot2_f32_f16 v157, v125, v58, v157
	v_dot2_f32_f16 v157, v124, v59, v157
	s_waitcnt lgkmcnt(0)
	v_dot2_f32_f16 v151, v127, v134, 0
	v_dot2_f32_f16 v151, v126, v135, v151
	v_dot2_f32_f16 v151, v125, v136, v151
	v_dot2_f32_f16 v151, v124, v137, v151
	ds_read_b128 v[72:75], v114 offset:41984
	ds_read_b128 v[68:71], v114 offset:46080
	ds_read_b128 v[64:67], v114 offset:50176
	v_add_f32_dpp v151, v151, v151 quad_perm:[1,0,3,2] row_mask:0xf bank_mask:0xf bound_ctrl:1
	ds_read_b128 v[60:63], v114 offset:29696
	ds_read_b128 v[56:59], v114 offset:54272
	v_add_f32_dpp v151, v151, v151 quad_perm:[2,3,0,1] row_mask:0xf bank_mask:0xf bound_ctrl:1
	ds_read_b32 v85, v115 offset:1536
	ds_write_b32 v116, v157 offset:8192
	v_add_f32_dpp v151, v151, v151 row_half_mirror row_mask:0xf bank_mask:0xf bound_ctrl:1
	v_cvt_pkrtz_f16_f32 v152, -v151, -v151
	v_pk_mul_f16 v153, v152, v138
	v_pk_mul_f16 v154, v152, v139
	v_pk_mul_f16 v155, v152, v140
	v_pk_mul_f16 v156, v152, v141
	v_pk_fma_f16 v153, v160, v142, v153
	v_pk_fma_f16 v154, v160, v143, v154
	v_pk_fma_f16 v155, v160, v144, v155
	v_pk_fma_f16 v156, v160, v145, v156
	v_pk_fma_f16 v127, v127, v130, v153
	v_pk_fma_f16 v126, v126, v131, v154
	v_pk_fma_f16 v125, v125, v132, v155
	v_pk_fma_f16 v124, v124, v133, v156
	v_dot2_f32_f16 v158, v127, v146, 0
	v_dot2_f32_f16 v158, v126, v147, v158
	v_dot2_f32_f16 v158, v125, v148, v158
	v_dot2_f32_f16 v158, v124, v149, v158
	s_waitcnt lgkmcnt(0)
	v_dot2_f32_f16 v151, v127, v72, 0
	v_dot2_f32_f16 v151, v126, v73, v151
	v_dot2_f32_f16 v151, v125, v74, v151
	v_dot2_f32_f16 v151, v124, v75, v151
	ds_read_b128 v[134:137], v114 offset:42112
	ds_read_b128 v[138:141], v114 offset:46208
	ds_read_b128 v[142:145], v114 offset:50304
	v_add_f32_dpp v151, v151, v151 quad_perm:[1,0,3,2] row_mask:0xf bank_mask:0xf bound_ctrl:1
	ds_read_b128 v[130:133], v114 offset:29824
	ds_read_b128 v[146:149], v114 offset:54400
	v_add_f32_dpp v151, v151, v151 quad_perm:[2,3,0,1] row_mask:0xf bank_mask:0xf bound_ctrl:1
	ds_read_b32 v160, v115 offset:1792
	ds_write_b32 v116, v158 offset:10240
	v_add_f32_dpp v151, v151, v151 row_half_mirror row_mask:0xf bank_mask:0xf bound_ctrl:1
	v_cvt_pkrtz_f16_f32 v152, -v151, -v151
	v_pk_mul_f16 v153, v152, v68
	v_pk_mul_f16 v154, v152, v69
	v_pk_mul_f16 v155, v152, v70
	v_pk_mul_f16 v156, v152, v71
	v_pk_fma_f16 v153, v85, v64, v153
	v_pk_fma_f16 v154, v85, v65, v154
	v_pk_fma_f16 v155, v85, v66, v155
	v_pk_fma_f16 v156, v85, v67, v156
	v_pk_fma_f16 v127, v127, v60, v153
	v_pk_fma_f16 v126, v126, v61, v154
	v_pk_fma_f16 v125, v125, v62, v155
	v_pk_fma_f16 v124, v124, v63, v156
	v_dot2_f32_f16 v157, v127, v56, 0
	v_dot2_f32_f16 v157, v126, v57, v157
	v_dot2_f32_f16 v157, v125, v58, v157
	v_dot2_f32_f16 v157, v124, v59, v157
	s_waitcnt lgkmcnt(0)
	v_dot2_f32_f16 v151, v127, v134, 0
	v_dot2_f32_f16 v151, v126, v135, v151
	v_dot2_f32_f16 v151, v125, v136, v151
	v_dot2_f32_f16 v151, v124, v137, v151
	ds_read_b128 v[72:75], v114 offset:42240
	ds_read_b128 v[68:71], v114 offset:46336
	ds_read_b128 v[64:67], v114 offset:50432
	v_add_f32_dpp v151, v151, v151 quad_perm:[1,0,3,2] row_mask:0xf bank_mask:0xf bound_ctrl:1
	ds_read_b128 v[60:63], v114 offset:29952
	ds_read_b128 v[56:59], v114 offset:54528
	v_add_f32_dpp v151, v151, v151 quad_perm:[2,3,0,1] row_mask:0xf bank_mask:0xf bound_ctrl:1
	ds_read_b32 v85, v115 offset:2048
	ds_write_b32 v116, v157 offset:12288
	v_add_f32_dpp v151, v151, v151 row_half_mirror row_mask:0xf bank_mask:0xf bound_ctrl:1
	v_cvt_pkrtz_f16_f32 v152, -v151, -v151
	v_pk_mul_f16 v153, v152, v138
	v_pk_mul_f16 v154, v152, v139
	v_pk_mul_f16 v155, v152, v140
	v_pk_mul_f16 v156, v152, v141
	v_pk_fma_f16 v153, v160, v142, v153
	v_pk_fma_f16 v154, v160, v143, v154
	v_pk_fma_f16 v155, v160, v144, v155
	v_pk_fma_f16 v156, v160, v145, v156
	v_pk_fma_f16 v127, v127, v130, v153
	v_pk_fma_f16 v126, v126, v131, v154
	v_pk_fma_f16 v125, v125, v132, v155
	v_pk_fma_f16 v124, v124, v133, v156
	v_dot2_f32_f16 v158, v127, v146, 0
	v_dot2_f32_f16 v158, v126, v147, v158
	v_dot2_f32_f16 v158, v125, v148, v158
	v_dot2_f32_f16 v158, v124, v149, v158
	s_waitcnt lgkmcnt(0)
	v_dot2_f32_f16 v151, v127, v72, 0
	v_dot2_f32_f16 v151, v126, v73, v151
	v_dot2_f32_f16 v151, v125, v74, v151
	v_dot2_f32_f16 v151, v124, v75, v151
	ds_read_b128 v[134:137], v114 offset:42368
	ds_read_b128 v[138:141], v114 offset:46464
	ds_read_b128 v[142:145], v114 offset:50560
	v_add_f32_dpp v151, v151, v151 quad_perm:[1,0,3,2] row_mask:0xf bank_mask:0xf bound_ctrl:1
	ds_read_b128 v[130:133], v114 offset:30080
	ds_read_b128 v[146:149], v114 offset:54656
	v_add_f32_dpp v151, v151, v151 quad_perm:[2,3,0,1] row_mask:0xf bank_mask:0xf bound_ctrl:1
	ds_read_b32 v160, v115 offset:2304
	ds_write_b32 v116, v158 offset:14336
	v_add_f32_dpp v151, v151, v151 row_half_mirror row_mask:0xf bank_mask:0xf bound_ctrl:1
	v_cvt_pkrtz_f16_f32 v152, -v151, -v151
	v_pk_mul_f16 v153, v152, v68
	v_pk_mul_f16 v154, v152, v69
	v_pk_mul_f16 v155, v152, v70
	v_pk_mul_f16 v156, v152, v71
	v_pk_fma_f16 v153, v85, v64, v153
	v_pk_fma_f16 v154, v85, v65, v154
	v_pk_fma_f16 v155, v85, v66, v155
	v_pk_fma_f16 v156, v85, v67, v156
	v_pk_fma_f16 v127, v127, v60, v153
	v_pk_fma_f16 v126, v126, v61, v154
	v_pk_fma_f16 v125, v125, v62, v155
	v_pk_fma_f16 v124, v124, v63, v156
	v_dot2_f32_f16 v157, v127, v56, 0
	v_dot2_f32_f16 v157, v126, v57, v157
	v_dot2_f32_f16 v157, v125, v58, v157
	v_dot2_f32_f16 v157, v124, v59, v157
	s_waitcnt lgkmcnt(0)
	v_dot2_f32_f16 v151, v127, v134, 0
	v_dot2_f32_f16 v151, v126, v135, v151
	v_dot2_f32_f16 v151, v125, v136, v151
	v_dot2_f32_f16 v151, v124, v137, v151
	ds_read_b128 v[72:75], v114 offset:42496
	ds_read_b128 v[68:71], v114 offset:46592
	ds_read_b128 v[64:67], v114 offset:50688
	v_add_f32_dpp v151, v151, v151 quad_perm:[1,0,3,2] row_mask:0xf bank_mask:0xf bound_ctrl:1
	ds_read_b128 v[60:63], v114 offset:30208
	ds_read_b128 v[56:59], v114 offset:54784
	v_add_f32_dpp v151, v151, v151 quad_perm:[2,3,0,1] row_mask:0xf bank_mask:0xf bound_ctrl:1
	ds_read_b32 v85, v115 offset:2560
	ds_write_b32 v116, v157 offset:16384
	v_add_f32_dpp v151, v151, v151 row_half_mirror row_mask:0xf bank_mask:0xf bound_ctrl:1
	v_cvt_pkrtz_f16_f32 v152, -v151, -v151
	v_pk_mul_f16 v153, v152, v138
	v_pk_mul_f16 v154, v152, v139
	v_pk_mul_f16 v155, v152, v140
	v_pk_mul_f16 v156, v152, v141
	v_pk_fma_f16 v153, v160, v142, v153
	v_pk_fma_f16 v154, v160, v143, v154
	v_pk_fma_f16 v155, v160, v144, v155
	v_pk_fma_f16 v156, v160, v145, v156
	v_pk_fma_f16 v127, v127, v130, v153
	v_pk_fma_f16 v126, v126, v131, v154
	v_pk_fma_f16 v125, v125, v132, v155
	v_pk_fma_f16 v124, v124, v133, v156
	v_dot2_f32_f16 v158, v127, v146, 0
	v_dot2_f32_f16 v158, v126, v147, v158
	v_dot2_f32_f16 v158, v125, v148, v158
	v_dot2_f32_f16 v158, v124, v149, v158
	s_waitcnt lgkmcnt(0)
	v_dot2_f32_f16 v151, v127, v72, 0
	v_dot2_f32_f16 v151, v126, v73, v151
	v_dot2_f32_f16 v151, v125, v74, v151
	v_dot2_f32_f16 v151, v124, v75, v151
	ds_read_b128 v[134:137], v114 offset:42624
	ds_read_b128 v[138:141], v114 offset:46720
	ds_read_b128 v[142:145], v114 offset:50816
	v_add_f32_dpp v151, v151, v151 quad_perm:[1,0,3,2] row_mask:0xf bank_mask:0xf bound_ctrl:1
	ds_read_b128 v[130:133], v114 offset:30336
	ds_read_b128 v[146:149], v114 offset:54912
	v_add_f32_dpp v151, v151, v151 quad_perm:[2,3,0,1] row_mask:0xf bank_mask:0xf bound_ctrl:1
	ds_read_b32 v160, v115 offset:2816
	ds_write_b32 v116, v158 offset:18432
	v_add_f32_dpp v151, v151, v151 row_half_mirror row_mask:0xf bank_mask:0xf bound_ctrl:1
	v_cvt_pkrtz_f16_f32 v152, -v151, -v151
	v_pk_mul_f16 v153, v152, v68
	v_pk_mul_f16 v154, v152, v69
	v_pk_mul_f16 v155, v152, v70
	v_pk_mul_f16 v156, v152, v71
	v_pk_fma_f16 v153, v85, v64, v153
	v_pk_fma_f16 v154, v85, v65, v154
	v_pk_fma_f16 v155, v85, v66, v155
	v_pk_fma_f16 v156, v85, v67, v156
	v_pk_fma_f16 v127, v127, v60, v153
	v_pk_fma_f16 v126, v126, v61, v154
	v_pk_fma_f16 v125, v125, v62, v155
	v_pk_fma_f16 v124, v124, v63, v156
	v_dot2_f32_f16 v157, v127, v56, 0
	v_dot2_f32_f16 v157, v126, v57, v157
	v_dot2_f32_f16 v157, v125, v58, v157
	v_dot2_f32_f16 v157, v124, v59, v157
	s_waitcnt lgkmcnt(0)
	v_dot2_f32_f16 v151, v127, v134, 0
	v_dot2_f32_f16 v151, v126, v135, v151
	v_dot2_f32_f16 v151, v125, v136, v151
	v_dot2_f32_f16 v151, v124, v137, v151
	ds_read_b128 v[72:75], v114 offset:42752
	ds_read_b128 v[68:71], v114 offset:46848
	ds_read_b128 v[64:67], v114 offset:50944
	v_add_f32_dpp v151, v151, v151 quad_perm:[1,0,3,2] row_mask:0xf bank_mask:0xf bound_ctrl:1
	ds_read_b128 v[60:63], v114 offset:30464
	ds_read_b128 v[56:59], v114 offset:55040
	v_add_f32_dpp v151, v151, v151 quad_perm:[2,3,0,1] row_mask:0xf bank_mask:0xf bound_ctrl:1
	ds_read_b32 v85, v115 offset:3072
	ds_write_b32 v116, v157 offset:20480
	v_add_f32_dpp v151, v151, v151 row_half_mirror row_mask:0xf bank_mask:0xf bound_ctrl:1
	v_cvt_pkrtz_f16_f32 v152, -v151, -v151
	v_pk_mul_f16 v153, v152, v138
	v_pk_mul_f16 v154, v152, v139
	v_pk_mul_f16 v155, v152, v140
	v_pk_mul_f16 v156, v152, v141
	v_pk_fma_f16 v153, v160, v142, v153
	v_pk_fma_f16 v154, v160, v143, v154
	v_pk_fma_f16 v155, v160, v144, v155
	v_pk_fma_f16 v156, v160, v145, v156
	v_pk_fma_f16 v127, v127, v130, v153
	v_pk_fma_f16 v126, v126, v131, v154
	v_pk_fma_f16 v125, v125, v132, v155
	v_pk_fma_f16 v124, v124, v133, v156
	v_dot2_f32_f16 v158, v127, v146, 0
	v_dot2_f32_f16 v158, v126, v147, v158
	v_dot2_f32_f16 v158, v125, v148, v158
	v_dot2_f32_f16 v158, v124, v149, v158
	s_waitcnt lgkmcnt(0)
	v_dot2_f32_f16 v151, v127, v72, 0
	v_dot2_f32_f16 v151, v126, v73, v151
	v_dot2_f32_f16 v151, v125, v74, v151
	v_dot2_f32_f16 v151, v124, v75, v151
	ds_read_b128 v[134:137], v114 offset:42880
	ds_read_b128 v[138:141], v114 offset:46976
	ds_read_b128 v[142:145], v114 offset:51072
	v_add_f32_dpp v151, v151, v151 quad_perm:[1,0,3,2] row_mask:0xf bank_mask:0xf bound_ctrl:1
	ds_read_b128 v[130:133], v114 offset:30592
	ds_read_b128 v[146:149], v114 offset:55168
	v_add_f32_dpp v151, v151, v151 quad_perm:[2,3,0,1] row_mask:0xf bank_mask:0xf bound_ctrl:1
	ds_read_b32 v160, v115 offset:3328
	ds_write_b32 v116, v158 offset:22528
	v_add_f32_dpp v151, v151, v151 row_half_mirror row_mask:0xf bank_mask:0xf bound_ctrl:1
	v_cvt_pkrtz_f16_f32 v152, -v151, -v151
	v_pk_mul_f16 v153, v152, v68
	v_pk_mul_f16 v154, v152, v69
	v_pk_mul_f16 v155, v152, v70
	v_pk_mul_f16 v156, v152, v71
	v_pk_fma_f16 v153, v85, v64, v153
	v_pk_fma_f16 v154, v85, v65, v154
	v_pk_fma_f16 v155, v85, v66, v155
	v_pk_fma_f16 v156, v85, v67, v156
	v_pk_fma_f16 v127, v127, v60, v153
	v_pk_fma_f16 v126, v126, v61, v154
	v_pk_fma_f16 v125, v125, v62, v155
	v_pk_fma_f16 v124, v124, v63, v156
	v_dot2_f32_f16 v157, v127, v56, 0
	v_dot2_f32_f16 v157, v126, v57, v157
	v_dot2_f32_f16 v157, v125, v58, v157
	v_dot2_f32_f16 v157, v124, v59, v157
	s_waitcnt lgkmcnt(0)
	v_dot2_f32_f16 v151, v127, v134, 0
	v_dot2_f32_f16 v151, v126, v135, v151
	v_dot2_f32_f16 v151, v125, v136, v151
	v_dot2_f32_f16 v151, v124, v137, v151
	ds_read_b128 v[72:75], v114 offset:43008
	ds_read_b128 v[68:71], v114 offset:47104
	ds_read_b128 v[64:67], v114 offset:51200
	v_add_f32_dpp v151, v151, v151 quad_perm:[1,0,3,2] row_mask:0xf bank_mask:0xf bound_ctrl:1
	ds_read_b128 v[60:63], v114 offset:30720
	ds_read_b128 v[56:59], v114 offset:55296
	v_add_f32_dpp v151, v151, v151 quad_perm:[2,3,0,1] row_mask:0xf bank_mask:0xf bound_ctrl:1
	ds_read_b32 v85, v115 offset:3584
	ds_write_b32 v116, v157 offset:24576
	v_add_f32_dpp v151, v151, v151 row_half_mirror row_mask:0xf bank_mask:0xf bound_ctrl:1
	v_cvt_pkrtz_f16_f32 v152, -v151, -v151
	v_pk_mul_f16 v153, v152, v138
	v_pk_mul_f16 v154, v152, v139
	v_pk_mul_f16 v155, v152, v140
	v_pk_mul_f16 v156, v152, v141
	v_pk_fma_f16 v153, v160, v142, v153
	v_pk_fma_f16 v154, v160, v143, v154
	v_pk_fma_f16 v155, v160, v144, v155
	v_pk_fma_f16 v156, v160, v145, v156
	v_pk_fma_f16 v127, v127, v130, v153
	v_pk_fma_f16 v126, v126, v131, v154
	v_pk_fma_f16 v125, v125, v132, v155
	v_pk_fma_f16 v124, v124, v133, v156
	v_dot2_f32_f16 v158, v127, v146, 0
	v_dot2_f32_f16 v158, v126, v147, v158
	v_dot2_f32_f16 v158, v125, v148, v158
	v_dot2_f32_f16 v158, v124, v149, v158
	s_waitcnt lgkmcnt(0)
	v_dot2_f32_f16 v151, v127, v72, 0
	v_dot2_f32_f16 v151, v126, v73, v151
	v_dot2_f32_f16 v151, v125, v74, v151
	v_dot2_f32_f16 v151, v124, v75, v151
	ds_read_b128 v[134:137], v114 offset:43136
	ds_read_b128 v[138:141], v114 offset:47232
	ds_read_b128 v[142:145], v114 offset:51328
	v_add_f32_dpp v151, v151, v151 quad_perm:[1,0,3,2] row_mask:0xf bank_mask:0xf bound_ctrl:1
	ds_read_b128 v[130:133], v114 offset:30848
	ds_read_b128 v[146:149], v114 offset:55424
	v_add_f32_dpp v151, v151, v151 quad_perm:[2,3,0,1] row_mask:0xf bank_mask:0xf bound_ctrl:1
	ds_read_b32 v160, v115 offset:3840
	ds_write_b32 v116, v158 offset:26624
	v_add_f32_dpp v151, v151, v151 row_half_mirror row_mask:0xf bank_mask:0xf bound_ctrl:1
	v_cvt_pkrtz_f16_f32 v152, -v151, -v151
	v_pk_mul_f16 v153, v152, v68
	v_pk_mul_f16 v154, v152, v69
	v_pk_mul_f16 v155, v152, v70
	v_pk_mul_f16 v156, v152, v71
	v_pk_fma_f16 v153, v85, v64, v153
	v_pk_fma_f16 v154, v85, v65, v154
	v_pk_fma_f16 v155, v85, v66, v155
	v_pk_fma_f16 v156, v85, v67, v156
	v_pk_fma_f16 v127, v127, v60, v153
	v_pk_fma_f16 v126, v126, v61, v154
	v_pk_fma_f16 v125, v125, v62, v155
	v_pk_fma_f16 v124, v124, v63, v156
	v_dot2_f32_f16 v157, v127, v56, 0
	v_dot2_f32_f16 v157, v126, v57, v157
	v_dot2_f32_f16 v157, v125, v58, v157
	v_dot2_f32_f16 v157, v124, v59, v157
	s_waitcnt lgkmcnt(0)
	v_dot2_f32_f16 v151, v127, v134, 0
	v_dot2_f32_f16 v151, v126, v135, v151
	v_dot2_f32_f16 v151, v125, v136, v151
	v_dot2_f32_f16 v151, v124, v137, v151
	s_nop 2
	v_add_f32_dpp v151, v151, v151 quad_perm:[1,0,3,2] row_mask:0xf bank_mask:0xf bound_ctrl:1
	s_nop 1
	v_add_f32_dpp v151, v151, v151 quad_perm:[2,3,0,1] row_mask:0xf bank_mask:0xf bound_ctrl:1
	s_nop 0
	ds_write_b32 v116, v157 offset:28672
	v_add_f32_dpp v151, v151, v151 row_half_mirror row_mask:0xf bank_mask:0xf bound_ctrl:1
	v_cvt_pkrtz_f16_f32 v152, -v151, -v151
	v_pk_mul_f16 v153, v152, v138
	v_pk_mul_f16 v154, v152, v139
	v_pk_mul_f16 v155, v152, v140
	v_pk_mul_f16 v156, v152, v141
	v_pk_fma_f16 v153, v160, v142, v153
	v_pk_fma_f16 v154, v160, v143, v154
	v_pk_fma_f16 v155, v160, v144, v155
	v_pk_fma_f16 v156, v160, v145, v156
	v_pk_fma_f16 v127, v127, v130, v153
	v_pk_fma_f16 v126, v126, v131, v154
	v_pk_fma_f16 v125, v125, v132, v155
	v_pk_fma_f16 v124, v124, v133, v156
	v_dot2_f32_f16 v158, v127, v146, 0
	v_dot2_f32_f16 v158, v126, v147, v158
	v_dot2_f32_f16 v158, v125, v148, v158
	v_dot2_f32_f16 v158, v124, v149, v158
	s_nop 2
	ds_write_b32 v116, v158 offset:30720
	s_waitcnt lgkmcnt(0)
	s_barrier
	s_waitcnt lgkmcnt(1)
	ds_read_b128 v[56:59], v94 offset:57856
	ds_read_b128 v[60:63], v94 offset:57872
	ds_read_b128 v[64:67], v94 offset:57888
	ds_read_b128 v[68:71], v94 offset:57904
	s_waitcnt lgkmcnt(3)
	v_add_f32_e32 v56, v56, v57
	v_add_f32_e32 v57, v58, v59
	v_add_f32_e32 v56, v56, v57
	s_waitcnt lgkmcnt(2)
	v_add_f32_e32 v57, v60, v61
	v_add_f32_e32 v58, v62, v63
	v_add_f32_e32 v57, v57, v58
	v_add_f32_e32 v56, v56, v57
	s_waitcnt lgkmcnt(1)
	v_add_f32_e32 v57, v64, v65
	v_add_f32_e32 v58, v66, v67
	v_add_f32_e32 v57, v57, v58
	s_waitcnt lgkmcnt(0)
	v_add_f32_e32 v58, v68, v69
	v_add_f32_e32 v59, v70, v71
	v_add_f32_e32 v58, v58, v59
	v_add_f32_e32 v57, v57, v58
	v_add_f32_e32 v58, v56, v57
	s_nop 1
	v_add_f32_dpp v58, v58, v58 quad_perm:[1,0,3,2] row_mask:0xf bank_mask:0xf bound_ctrl:1
	s_nop 1
	v_add_f32_dpp v58, v58, v58 quad_perm:[2,3,0,1] row_mask:0xf bank_mask:0xf bound_ctrl:1
	s_nop 1
	v_add_f32_dpp v58, v58, v58 row_half_mirror row_mask:0xf bank_mask:0xf bound_ctrl:1
	s_nop 1
	v_add_f32_dpp v58, v58, v58 row_mirror row_mask:0xf bank_mask:0xf bound_ctrl:1
	s_nop 0
	v_readlane_b32 s19, v58, 16
	v_readlane_b32 s23, v58, 48
	v_readlane_b32 s18, v58, 0
	v_readlane_b32 s22, v58, 32
	v_mov_b32_e32 v58, s19
	v_mov_b32_e32 v59, s23
	v_add_f32_e32 v58, s18, v58
	v_add_f32_e32 v59, s22, v59
	v_cndmask_b32_e64 v58, v59, v58, s[12:13]
	v_fmac_f32_e32 v57, 0xbc800000, v58
	v_fmac_f32_e32 v56, 0xbc800000, v58
	v_mul_f32_e32 v58, v57, v57
	v_fmac_f32_e32 v58, v56, v56
	s_nop 1
	v_add_f32_dpp v58, v58, v58 quad_perm:[1,0,3,2] row_mask:0xf bank_mask:0xf bound_ctrl:1
	s_nop 1
	v_add_f32_dpp v58, v58, v58 quad_perm:[2,3,0,1] row_mask:0xf bank_mask:0xf bound_ctrl:1
	s_nop 1
	v_add_f32_dpp v58, v58, v58 row_half_mirror row_mask:0xf bank_mask:0xf bound_ctrl:1
	s_nop 1
	v_add_f32_dpp v58, v58, v58 row_mirror row_mask:0xf bank_mask:0xf bound_ctrl:1
	s_nop 0
	v_readlane_b32 s22, v58, 0
	v_readlane_b32 s24, v58, 16
	v_readlane_b32 s23, v58, 32
	v_readlane_b32 s25, v58, 48
	s_and_saveexec_b64 s[18:19], s[16:17]
	s_cbranch_execz .LBB0_1242
	v_mov_b32_e32 v58, s24
	v_mov_b32_e32 v59, s25
	v_add_f32_e32 v58, s22, v58
	v_add_f32_e32 v59, s23, v59
	v_cndmask_b32_e64 v58, v59, v58, s[12:13]
	v_fmamk_f32 v58, v58, 0x3c800000, v120
	v_mul_f32_e32 v59, 0x4b800000, v58
	v_cmp_gt_f32_e32 vcc, s29, v58
	s_nop 1
	v_cndmask_b32_e32 v58, v58, v59, vcc
	v_rsq_f32_e32 v60, v58
	v_add_u32_e32 v165, s100, v121
	v_mov_b32_e32 v58, v162
	v_mov_b32_e32 v59, v163
	ds_read_b32 v105, v123 offset:57600
	ds_read_b64 v[62:63], v165 offset:37120
	v_mul_f32_e32 v61, 0x45800000, v60
	v_cndmask_b32_e32 v64, v60, v61, vcc
	v_mul_f32_e32 v60, v57, v64
	s_waitcnt lgkmcnt(2)
	v_mov_b32_e32 v61, v59
	s_waitcnt lgkmcnt(1)
	v_pk_mul_f32 v[60:61], v[104:105], v[60:61]
	v_mul_f32_e32 v56, v56, v64
	v_add_f32_e32 v57, v87, v60
	v_add_f32_e32 v57, v57, v61
	s_waitcnt lgkmcnt(0)
	v_mul_f32_e32 v59, v63, v57
	v_mov_b32_e32 v85, v105
	v_mov_b32_e32 v57, v58
	v_pk_mul_f32 v[56:57], v[84:85], v[56:57]
	s_nop 0
	v_add_f32_e32 v56, v86, v56
	v_add_f32_e32 v56, v56, v57
	v_mul_f32_e32 v56, v62, v56
	v_cvt_pk_bf16_f32 v58, v56, v59
	v_lshl_add_u32 v56, s4, 4, v95
	v_ashrrev_i32_e32 v57, 31, v56
	v_lshlrev_b64 v[56:57], 12, v[56:57]
	v_lshl_add_u64 v[56:57], v[106:107], 0, v[56:57]
	global_store_dword v[56:57], v58, off offset:2048
.LBB0_1242:
	s_or_b64 exec, exec, s[18:19]
	s_xor_b32 s100, s100, 0xe100
	s_cmpk_lg_i32 s30, 0x80
	s_cbranch_scc0 .LBB0_1250
	s_mov_b32 s4, s30
	s_and_saveexec_b64 s[18:19], s[10:11]
	s_cbranch_execnz .LBB0_1229
	s_branch .LBB0_1230

.LBB0_1249:
	v_mfma_f32_16x16x32_bf16 v[56:59], v[0:3], v[32:35], 0
	v_mfma_f32_16x16x32_bf16 v[56:59], v[4:7], v[36:39], v[56:59]
	v_mfma_f32_16x16x32_bf16 v[56:59], v[8:11], v[40:43], v[56:59]
	v_mfma_f32_16x16x32_bf16 v[56:59], v[12:15], v[44:47], v[56:59]
	v_add_u32_e32 v164, s100, v122
	s_nop 7
	ds_write_b128 v164, v[56:59] offset:37120
	s_andn2_saveexec_b64 s[22:23], s[22:23]
	s_cbranch_execnz .LBB0_1233
	s_branch .LBB0_1234
